# residual epilogues (out-proj, down-proj): 16 x-loads in flight with counted waits instead of one load per wait
# speedup vs baseline: 1.0128x; 1.0051x over previous
;     __device__ __forceinline__ void operator()(const f32x4 (&acc)[2][2][4][2], const Unit& u, int wr, int wc, int fr, int fq) const {
;         const int row0 = u.pm * BM + wr * 64 + fr, col0 = u.pn * BM + wc * 32 + 4 * fq; const int b = (u.pm * BM) >> 12;
;         f32x4 gv[2][2];
; #pragma unroll
;         for (int bj = 0; bj < 2; ++bj)
; #pragma unroll
;             for (int n = 0; n < 2; ++n) gv[bj][n] = *(const f32x4*)(gate + b * MODW + col0 + bj * HALF + n * 16);
; #pragma unroll
;         for (int ai = 0; ai < 2; ++ai)
; #pragma unroll
;             for (int m = 0; m < 4; ++m) { const size_t off = (size_t)(row0 + ai * HALF + m * 16) * DM + col0;
; #pragma unroll
;                 for (int bj = 0; bj < 2; ++bj)
; #pragma unroll
;                     for (int n = 0; n < 2; ++n) { const f32x4 bs = stream ? __builtin_nontemporal_load((const f32x4*)(xin + off + bj * HALF + n * 16)) : *(const f32x4*)(xin + off + bj * HALF + n * 16);
;                         *(f32x4*)(xout + off + bj * HALF + n * 16) = bs + gv[bj][n] * acc[ai][bj][m][n]; }
;                 if (m & 1) asm volatile("" ::: "memory"); }
.LBB0_822:
	s_lshr_b32 s15, s45, 4
	s_mul_i32 s24, s15, 0x3000
	v_lshl_add_u32 v150, s45, 8, v153
	v_lshl_or_b32 v148, s46, 8, v154
	s_ashr_i32 s25, s24, 31
	v_ashrrev_i32_e32 v151, 31, v150
	s_lshl_b64 s[24:25], s[24:25], 2
	v_ashrrev_i32_e32 v149, 31, v148
	v_lshlrev_b64 v[146:147], 11, v[150:151]
	s_add_u32 s24, s20, s24
	v_lshl_add_u64 v[146:147], v[146:147], 0, v[148:149]
	s_addc_u32 s25, s21, s25
	v_lshlrev_b64 v[146:147], 2, v[146:147]
	v_lshl_add_u64 v[126:127], v[148:149], 2, s[24:25]
	v_lshl_add_u64 v[162:163], s[48:49], 0, v[146:147]
	global_load_dwordx4 v[142:145], v[126:127], off
	global_load_dwordx4 v[134:137], v[126:127], off offset:64
	global_load_dwordx4 v[130:133], v[126:127], off offset:512
	s_nop 0
	global_load_dwordx4 v[126:129], v[126:127], off offset:576
	v_readlane_b32 s56, v250, 5
	s_andn2_b64 vcc, exec, s[16:17]
	v_readlane_b32 s57, v250, 6
	v_readlane_b32 s55, v250, 7
	s_mov_b64 s[24:25], s[48:49]
	global_load_dwordx4 v[218:221], v146, s[24:25]
	global_load_dwordx4 v[222:225], v146, s[24:25] offset:64
	global_load_dwordx4 v[226:229], v146, s[24:25] offset:512
	global_load_dwordx4 v[230:233], v146, s[24:25] offset:576
	s_add_u32 s24, s48, 0x20000
	s_addc_u32 s25, s49, 0
	global_load_dwordx4 v[234:237], v146, s[24:25]
	global_load_dwordx4 v[238:241], v146, s[24:25] offset:64
	global_load_dwordx4 v[242:245], v146, s[24:25] offset:512
	global_load_dwordx4 v[246:249], v146, s[24:25] offset:576
	s_add_u32 s24, s48, 0x40000
	s_addc_u32 s25, s49, 0
	global_load_dwordx4 v[158:161], v146, s[24:25]
	global_load_dwordx4 v[162:165], v146, s[24:25] offset:64
	global_load_dwordx4 v[166:169], v146, s[24:25] offset:512
	global_load_dwordx4 v[170:173], v146, s[24:25] offset:576
	s_add_u32 s24, s48, 0x60000
	s_addc_u32 s25, s49, 0
	global_load_dwordx4 v[174:177], v146, s[24:25]
	global_load_dwordx4 v[182:185], v146, s[24:25] offset:64
	global_load_dwordx4 v[186:189], v146, s[24:25] offset:512
	global_load_dwordx4 v[190:193], v146, s[24:25] offset:576
	s_mov_b64 s[100:101], s[70:71]
	s_waitcnt vmcnt(15)
	v_pk_fma_f32 v[140:141], v[140:141], v[144:145], v[220:221]
	v_pk_fma_f32 v[138:139], v[138:139], v[142:143], v[218:219]
	global_store_dwordx4 v146, v[138:141], s[100:101]
	s_add_u32 s24, s48, 0x100000
	s_addc_u32 s25, s49, 0
	global_load_dwordx4 v[218:221], v146, s[24:25]
	s_waitcnt vmcnt(15)
	v_pk_fma_f32 v[124:125], v[124:125], v[136:137], v[224:225]
	v_pk_fma_f32 v[122:123], v[122:123], v[134:135], v[222:223]
	global_store_dwordx4 v146, v[122:125], s[100:101] offset:64
	global_load_dwordx4 v[222:225], v146, s[24:25] offset:64
	s_waitcnt vmcnt(15)
	v_pk_fma_f32 v[120:121], v[120:121], v[132:133], v[228:229]
	v_pk_fma_f32 v[118:119], v[118:119], v[130:131], v[226:227]
	global_store_dwordx4 v146, v[118:121], s[100:101] offset:512
	global_load_dwordx4 v[226:229], v146, s[24:25] offset:512
	s_waitcnt vmcnt(15)
	v_pk_fma_f32 v[116:117], v[116:117], v[128:129], v[232:233]
	v_pk_fma_f32 v[114:115], v[114:115], v[126:127], v[230:231]
	global_store_dwordx4 v146, v[114:117], s[100:101] offset:576
	global_load_dwordx4 v[230:233], v146, s[24:25] offset:576
	s_add_u32 s100, s70, 0x20000
	s_addc_u32 s101, s71, 0
	s_waitcnt vmcnt(15)
	v_pk_fma_f32 v[112:113], v[112:113], v[144:145], v[236:237]
	v_pk_fma_f32 v[110:111], v[110:111], v[142:143], v[234:235]
	global_store_dwordx4 v146, v[110:113], s[100:101]
	s_add_u32 s24, s48, 0x120000
	s_addc_u32 s25, s49, 0
	global_load_dwordx4 v[234:237], v146, s[24:25]
	s_waitcnt vmcnt(15)
	v_pk_fma_f32 v[108:109], v[108:109], v[136:137], v[240:241]
	v_pk_fma_f32 v[106:107], v[106:107], v[134:135], v[238:239]
	global_store_dwordx4 v146, v[106:109], s[100:101] offset:64
	global_load_dwordx4 v[238:241], v146, s[24:25] offset:64
	s_waitcnt vmcnt(15)
	v_pk_fma_f32 v[104:105], v[104:105], v[132:133], v[244:245]
	v_pk_fma_f32 v[102:103], v[102:103], v[130:131], v[242:243]
	global_store_dwordx4 v146, v[102:105], s[100:101] offset:512
	global_load_dwordx4 v[242:245], v146, s[24:25] offset:512
	s_waitcnt vmcnt(15)
	v_pk_fma_f32 v[100:101], v[100:101], v[128:129], v[248:249]
	v_pk_fma_f32 v[98:99], v[98:99], v[126:127], v[246:247]
	global_store_dwordx4 v146, v[98:101], s[100:101] offset:576
	global_load_dwordx4 v[246:249], v146, s[24:25] offset:576
	s_add_u32 s100, s70, 0x40000
	s_addc_u32 s101, s71, 0
	s_waitcnt vmcnt(15)
	v_pk_fma_f32 v[96:97], v[96:97], v[144:145], v[160:161]
	v_pk_fma_f32 v[94:95], v[94:95], v[142:143], v[158:159]
	global_store_dwordx4 v146, v[94:97], s[100:101]
	s_add_u32 s24, s48, 0x140000
	s_addc_u32 s25, s49, 0
	global_load_dwordx4 v[158:161], v146, s[24:25]
	s_waitcnt vmcnt(15)
	v_pk_fma_f32 v[92:93], v[92:93], v[136:137], v[164:165]
	v_pk_fma_f32 v[90:91], v[90:91], v[134:135], v[162:163]
	global_store_dwordx4 v146, v[90:93], s[100:101] offset:64
	global_load_dwordx4 v[162:165], v146, s[24:25] offset:64
	s_waitcnt vmcnt(15)
;     __device__ __forceinline__ void operator()(const f32x4 (&acc)[2][2][4][2], const Unit& u, int wr, int wc, int fr, int fq) const {
;     ...
;         for (int ai = 0; ai < 2; ++ai)
; #pragma unroll
;             for (int m = 0; m < 4; ++m) { const size_t off = (size_t)(row0 + ai * HALF + m * 16) * DM + col0;
; #pragma unroll
;                 for (int bj = 0; bj < 2; ++bj)
; #pragma unroll
;                     for (int n = 0; n < 2; ++n) { const f32x4 bs = stream ? __builtin_nontemporal_load((const f32x4*)(xin + off + bj * HALF + n * 16)) : *(const f32x4*)(xin + off + bj * HALF + n * 16);
;                         *(f32x4*)(xout + off + bj * HALF + n * 16) = bs + gv[bj][n] * acc[ai][bj][m][n]; }
;                 if (m & 1) asm volatile("" ::: "memory"); }
	v_pk_fma_f32 v[88:89], v[88:89], v[132:133], v[168:169]
	v_pk_fma_f32 v[86:87], v[86:87], v[130:131], v[166:167]
	global_store_dwordx4 v146, v[86:89], s[100:101] offset:512
	global_load_dwordx4 v[166:169], v146, s[24:25] offset:512
	s_waitcnt vmcnt(15)
	v_pk_fma_f32 v[84:85], v[84:85], v[128:129], v[172:173]
	v_pk_fma_f32 v[82:83], v[82:83], v[126:127], v[170:171]
	global_store_dwordx4 v146, v[82:85], s[100:101] offset:576
	global_load_dwordx4 v[170:173], v146, s[24:25] offset:576
	s_add_u32 s100, s70, 0x60000
	s_addc_u32 s101, s71, 0
	s_waitcnt vmcnt(15)
	v_pk_fma_f32 v[80:81], v[80:81], v[144:145], v[176:177]
	v_pk_fma_f32 v[78:79], v[78:79], v[142:143], v[174:175]
	global_store_dwordx4 v146, v[78:81], s[100:101]
	s_add_u32 s24, s48, 0x160000
	s_addc_u32 s25, s49, 0
	global_load_dwordx4 v[174:177], v146, s[24:25]
	s_waitcnt vmcnt(15)
	v_pk_fma_f32 v[76:77], v[76:77], v[136:137], v[184:185]
	v_pk_fma_f32 v[74:75], v[74:75], v[134:135], v[182:183]
	global_store_dwordx4 v146, v[74:77], s[100:101] offset:64
	global_load_dwordx4 v[182:185], v146, s[24:25] offset:64
	s_waitcnt vmcnt(15)
	v_pk_fma_f32 v[72:73], v[72:73], v[132:133], v[188:189]
	v_pk_fma_f32 v[70:71], v[70:71], v[130:131], v[186:187]
	global_store_dwordx4 v146, v[70:73], s[100:101] offset:512
	global_load_dwordx4 v[186:189], v146, s[24:25] offset:512
	s_waitcnt vmcnt(15)
	v_pk_fma_f32 v[68:69], v[68:69], v[128:129], v[192:193]
	v_pk_fma_f32 v[66:67], v[66:67], v[126:127], v[190:191]
	global_store_dwordx4 v146, v[66:69], s[100:101] offset:576
	global_load_dwordx4 v[190:193], v146, s[24:25] offset:576
	s_add_u32 s100, s70, 0x100000
	s_addc_u32 s101, s71, 0
	s_waitcnt vmcnt(15)
	v_pk_fma_f32 v[64:65], v[64:65], v[144:145], v[220:221]
	v_pk_fma_f32 v[62:63], v[62:63], v[142:143], v[218:219]
	global_store_dwordx4 v146, v[62:65], s[100:101]
	s_waitcnt vmcnt(14)
	v_pk_fma_f32 v[60:61], v[60:61], v[136:137], v[224:225]
	v_pk_fma_f32 v[58:59], v[58:59], v[134:135], v[222:223]
	global_store_dwordx4 v146, v[58:61], s[100:101] offset:64
	s_waitcnt vmcnt(13)
	v_pk_fma_f32 v[56:57], v[56:57], v[132:133], v[228:229]
	v_pk_fma_f32 v[54:55], v[54:55], v[130:131], v[226:227]
	global_store_dwordx4 v146, v[54:57], s[100:101] offset:512
	s_waitcnt vmcnt(12)
	v_pk_fma_f32 v[52:53], v[52:53], v[128:129], v[232:233]
	v_pk_fma_f32 v[50:51], v[50:51], v[126:127], v[230:231]
	global_store_dwordx4 v146, v[50:53], s[100:101] offset:576
	s_add_u32 s100, s70, 0x120000
	s_addc_u32 s101, s71, 0
	s_waitcnt vmcnt(11)
	v_pk_fma_f32 v[48:49], v[48:49], v[144:145], v[236:237]
	v_pk_fma_f32 v[46:47], v[46:47], v[142:143], v[234:235]
	global_store_dwordx4 v146, v[46:49], s[100:101]
	s_waitcnt vmcnt(10)
	v_pk_fma_f32 v[44:45], v[44:45], v[136:137], v[240:241]
	v_pk_fma_f32 v[42:43], v[42:43], v[134:135], v[238:239]
	global_store_dwordx4 v146, v[42:45], s[100:101] offset:64
	s_waitcnt vmcnt(9)
	v_pk_fma_f32 v[40:41], v[40:41], v[132:133], v[244:245]
	v_pk_fma_f32 v[38:39], v[38:39], v[130:131], v[242:243]
	global_store_dwordx4 v146, v[38:41], s[100:101] offset:512
	s_waitcnt vmcnt(8)
	v_pk_fma_f32 v[36:37], v[36:37], v[128:129], v[248:249]
	v_pk_fma_f32 v[34:35], v[34:35], v[126:127], v[246:247]
	global_store_dwordx4 v146, v[34:37], s[100:101] offset:576
	s_add_u32 s100, s70, 0x140000
	s_addc_u32 s101, s71, 0
	s_waitcnt vmcnt(7)
	v_pk_fma_f32 v[32:33], v[32:33], v[144:145], v[160:161]
	v_pk_fma_f32 v[30:31], v[30:31], v[142:143], v[158:159]
	global_store_dwordx4 v146, v[30:33], s[100:101]
	s_waitcnt vmcnt(6)
	v_pk_fma_f32 v[28:29], v[28:29], v[136:137], v[164:165]
	v_pk_fma_f32 v[26:27], v[26:27], v[134:135], v[162:163]
	global_store_dwordx4 v146, v[26:29], s[100:101] offset:64
	s_waitcnt vmcnt(5)
	v_pk_fma_f32 v[24:25], v[24:25], v[132:133], v[168:169]
	v_pk_fma_f32 v[22:23], v[22:23], v[130:131], v[166:167]
	global_store_dwordx4 v146, v[22:25], s[100:101] offset:512
	s_waitcnt vmcnt(4)
	v_pk_fma_f32 v[20:21], v[20:21], v[128:129], v[172:173]
	v_pk_fma_f32 v[18:19], v[18:19], v[126:127], v[170:171]
	global_store_dwordx4 v146, v[18:21], s[100:101] offset:576
	s_add_u32 s100, s70, 0x160000
	s_addc_u32 s101, s71, 0
	s_waitcnt vmcnt(3)
	v_pk_fma_f32 v[16:17], v[16:17], v[144:145], v[176:177]
	v_pk_fma_f32 v[14:15], v[14:15], v[142:143], v[174:175]
	global_store_dwordx4 v146, v[14:17], s[100:101]
	s_waitcnt vmcnt(2)
	v_pk_fma_f32 v[12:13], v[12:13], v[136:137], v[184:185]
	v_pk_fma_f32 v[10:11], v[10:11], v[134:135], v[182:183]
	global_store_dwordx4 v146, v[10:13], s[100:101] offset:64
	s_waitcnt vmcnt(1)
	v_pk_fma_f32 v[8:9], v[8:9], v[132:133], v[188:189]
	v_pk_fma_f32 v[6:7], v[6:7], v[130:131], v[186:187]
	global_store_dwordx4 v146, v[6:9], s[100:101] offset:512
	s_waitcnt vmcnt(0)
	v_pk_fma_f32 v[4:5], v[4:5], v[128:129], v[192:193]
	v_pk_fma_f32 v[2:3], v[2:3], v[126:127], v[190:191]
	global_store_dwordx4 v146, v[2:5], s[100:101] offset:576
	s_mov_b64 s[24:25], -1
	s_waitcnt vmcnt(0)
	s_cbranch_vccnz .LBB0_811
	s_andn2_b64 vcc, exec, s[0:1]
	s_cbranch_vccnz .LBB0_810
	s_barrier
	s_branch .LBB0_810

;     __device__ __forceinline__ void operator()(const f32x4 (&acc)[2][2][4][2], const Unit& u, int wr, int wc, int fr, int fq) const {
;         const int row0 = u.pm * BM + wr * 64 + fr, col0 = u.pn * BM + wc * 32 + 4 * fq; const int b = (u.pm * BM) >> 12;
;         f32x4 gv[2][2];
; #pragma unroll
;         for (int bj = 0; bj < 2; ++bj)
; #pragma unroll
;             for (int n = 0; n < 2; ++n) gv[bj][n] = *(const f32x4*)(gate + b * MODW + col0 + bj * HALF + n * 16);
; #pragma unroll
;         for (int ai = 0; ai < 2; ++ai)
; #pragma unroll
;             for (int m = 0; m < 4; ++m) { const size_t off = (size_t)(row0 + ai * HALF + m * 16) * DM + col0;
; #pragma unroll
;                 for (int bj = 0; bj < 2; ++bj)
; #pragma unroll
;                     for (int n = 0; n < 2; ++n) { const f32x4 bs = stream ? __builtin_nontemporal_load((const f32x4*)(xin + off + bj * HALF + n * 16)) : *(const f32x4*)(xin + off + bj * HALF + n * 16);
;                         *(f32x4*)(xout + off + bj * HALF + n * 16) = bs + gv[bj][n] * acc[ai][bj][m][n]; }
;                 if (m & 1) asm volatile("" ::: "memory"); }
.LBB0_1085:
	s_lshr_b32 s22, s44, 4
	s_mulk_i32 s22, 0x3000
	s_ashr_i32 s23, s22, 31
	v_lshl_add_u32 v150, s44, 8, v153
	v_lshl_or_b32 v74, s45, 8, v154
	s_lshl_b64 s[22:23], s[22:23], 2
	v_ashrrev_i32_e32 v151, 31, v150
	s_add_u32 s22, s20, s22
	v_ashrrev_i32_e32 v75, 31, v74
	v_lshlrev_b64 v[146:147], 13, v[150:151]
	s_addc_u32 s23, s21, s23
	v_lshlrev_b64 v[148:149], 2, v[74:75]
	v_lshl_add_u64 v[146:147], s[70:71], 0, v[146:147]
	v_lshl_add_u64 v[74:75], s[22:23], 0, v[148:149]
	v_lshl_add_u64 v[146:147], v[146:147], 0, v[148:149]
	global_load_dwordx4 v[94:97], v[74:75], off
	global_load_dwordx4 v[90:93], v[74:75], off offset:64
	global_load_dwordx4 v[86:89], v[74:75], off offset:512
	s_nop 0
	global_load_dwordx4 v[74:77], v[74:75], off offset:576
	s_mov_b64 s[34:35], 0x100
	s_mov_b64 s[52:53], 0x1d0000
	v_lshl_add_u32 v151, v150, 13, v148
	s_mov_b64 s[22:23], s[70:71]
	global_load_dwordx4 v[218:221], v151, s[22:23]
	global_load_dwordx4 v[222:225], v151, s[22:23] offset:64
	global_load_dwordx4 v[226:229], v151, s[22:23] offset:512
	global_load_dwordx4 v[230:233], v151, s[22:23] offset:576
	s_add_u32 s22, s70, 0x20000
	s_addc_u32 s23, s71, 0
	global_load_dwordx4 v[234:237], v151, s[22:23]
	global_load_dwordx4 v[238:241], v151, s[22:23] offset:64
	global_load_dwordx4 v[242:245], v151, s[22:23] offset:512
	global_load_dwordx4 v[246:249], v151, s[22:23] offset:576
	s_add_u32 s22, s70, 0x40000
	s_addc_u32 s23, s71, 0
	global_load_dwordx4 v[158:161], v151, s[22:23]
	global_load_dwordx4 v[162:165], v151, s[22:23] offset:64
	global_load_dwordx4 v[166:169], v151, s[22:23] offset:512
	global_load_dwordx4 v[170:173], v151, s[22:23] offset:576
	s_add_u32 s22, s70, 0x60000
	s_addc_u32 s23, s71, 0
	global_load_dwordx4 v[174:177], v151, s[22:23]
	global_load_dwordx4 v[182:185], v151, s[22:23] offset:64
	global_load_dwordx4 v[186:189], v151, s[22:23] offset:512
	global_load_dwordx4 v[190:193], v151, s[22:23] offset:576
	s_mov_b64 s[100:101], s[70:71]
	s_waitcnt vmcnt(15)
	v_pk_fma_f32 v[144:145], v[144:145], v[96:97], v[220:221]
	v_pk_fma_f32 v[142:143], v[142:143], v[94:95], v[218:219]
	global_store_dwordx4 v151, v[142:145], s[100:101]
	s_add_u32 s22, s70, 0x100000
	s_addc_u32 s23, s71, 0
	global_load_dwordx4 v[218:221], v151, s[22:23]
	s_waitcnt vmcnt(15)
	v_pk_fma_f32 v[140:141], v[140:141], v[92:93], v[224:225]
	v_pk_fma_f32 v[138:139], v[138:139], v[90:91], v[222:223]
	global_store_dwordx4 v151, v[138:141], s[100:101] offset:64
	global_load_dwordx4 v[222:225], v151, s[22:23] offset:64
	s_waitcnt vmcnt(15)
	v_pk_fma_f32 v[136:137], v[136:137], v[88:89], v[228:229]
	v_pk_fma_f32 v[134:135], v[134:135], v[86:87], v[226:227]
	global_store_dwordx4 v151, v[134:137], s[100:101] offset:512
	global_load_dwordx4 v[226:229], v151, s[22:23] offset:512
	s_waitcnt vmcnt(15)
	v_pk_fma_f32 v[132:133], v[132:133], v[76:77], v[232:233]
	v_pk_fma_f32 v[130:131], v[130:131], v[74:75], v[230:231]
	global_store_dwordx4 v151, v[130:133], s[100:101] offset:576
	global_load_dwordx4 v[230:233], v151, s[22:23] offset:576
	s_add_u32 s100, s70, 0x20000
	s_addc_u32 s101, s71, 0
	s_waitcnt vmcnt(15)
	v_pk_fma_f32 v[128:129], v[128:129], v[96:97], v[236:237]
	v_pk_fma_f32 v[126:127], v[126:127], v[94:95], v[234:235]
	global_store_dwordx4 v151, v[126:129], s[100:101]
	s_add_u32 s22, s70, 0x120000
	s_addc_u32 s23, s71, 0
	global_load_dwordx4 v[234:237], v151, s[22:23]
	s_waitcnt vmcnt(15)
	v_pk_fma_f32 v[124:125], v[124:125], v[92:93], v[240:241]
	v_pk_fma_f32 v[122:123], v[122:123], v[90:91], v[238:239]
	global_store_dwordx4 v151, v[122:125], s[100:101] offset:64
	global_load_dwordx4 v[238:241], v151, s[22:23] offset:64
	s_waitcnt vmcnt(15)
	v_pk_fma_f32 v[120:121], v[120:121], v[88:89], v[244:245]
	v_pk_fma_f32 v[118:119], v[118:119], v[86:87], v[242:243]
	global_store_dwordx4 v151, v[118:121], s[100:101] offset:512
	global_load_dwordx4 v[242:245], v151, s[22:23] offset:512
	s_waitcnt vmcnt(15)
	v_pk_fma_f32 v[116:117], v[116:117], v[76:77], v[248:249]
	v_pk_fma_f32 v[114:115], v[114:115], v[74:75], v[246:247]
	global_store_dwordx4 v151, v[114:117], s[100:101] offset:576
	global_load_dwordx4 v[246:249], v151, s[22:23] offset:576
	s_add_u32 s100, s70, 0x40000
	s_addc_u32 s101, s71, 0
	s_waitcnt vmcnt(15)
	v_pk_fma_f32 v[112:113], v[112:113], v[96:97], v[160:161]
	v_pk_fma_f32 v[110:111], v[110:111], v[94:95], v[158:159]
	global_store_dwordx4 v151, v[110:113], s[100:101]
	s_add_u32 s22, s70, 0x140000
	s_addc_u32 s23, s71, 0
	global_load_dwordx4 v[158:161], v151, s[22:23]
	s_waitcnt vmcnt(15)
	v_pk_fma_f32 v[108:109], v[108:109], v[92:93], v[164:165]
	v_pk_fma_f32 v[106:107], v[106:107], v[90:91], v[162:163]
	global_store_dwordx4 v151, v[106:109], s[100:101] offset:64
	global_load_dwordx4 v[162:165], v151, s[22:23] offset:64
	s_waitcnt vmcnt(15)
;     __device__ __forceinline__ void operator()(const f32x4 (&acc)[2][2][4][2], const Unit& u, int wr, int wc, int fr, int fq) const {
;     ...
;             for (int m = 0; m < 4; ++m) { const size_t off = (size_t)(row0 + ai * HALF + m * 16) * DM + col0;
; #pragma unroll
;                 for (int bj = 0; bj < 2; ++bj)
; #pragma unroll
;                     for (int n = 0; n < 2; ++n) { const f32x4 bs = stream ? __builtin_nontemporal_load((const f32x4*)(xin + off + bj * HALF + n * 16)) : *(const f32x4*)(xin + off + bj * HALF + n * 16);
;                         *(f32x4*)(xout + off + bj * HALF + n * 16) = bs + gv[bj][n] * acc[ai][bj][m][n]; }
;                 if (m & 1) asm volatile("" ::: "memory"); }
	v_pk_fma_f32 v[104:105], v[104:105], v[88:89], v[168:169]
	v_pk_fma_f32 v[102:103], v[102:103], v[86:87], v[166:167]
	global_store_dwordx4 v151, v[102:105], s[100:101] offset:512
	global_load_dwordx4 v[166:169], v151, s[22:23] offset:512
	s_waitcnt vmcnt(15)
	v_pk_fma_f32 v[100:101], v[100:101], v[76:77], v[172:173]
	v_pk_fma_f32 v[98:99], v[98:99], v[74:75], v[170:171]
	global_store_dwordx4 v151, v[98:101], s[100:101] offset:576
	global_load_dwordx4 v[170:173], v151, s[22:23] offset:576
	s_add_u32 s100, s70, 0x60000
	s_addc_u32 s101, s71, 0
	s_waitcnt vmcnt(15)
	v_pk_fma_f32 v[84:85], v[84:85], v[96:97], v[176:177]
	v_pk_fma_f32 v[82:83], v[82:83], v[94:95], v[174:175]
	global_store_dwordx4 v151, v[82:85], s[100:101]
	s_add_u32 s22, s70, 0x160000
	s_addc_u32 s23, s71, 0
	global_load_dwordx4 v[174:177], v151, s[22:23]
	s_waitcnt vmcnt(15)
	v_pk_fma_f32 v[80:81], v[80:81], v[92:93], v[184:185]
	v_pk_fma_f32 v[78:79], v[78:79], v[90:91], v[182:183]
	global_store_dwordx4 v151, v[78:81], s[100:101] offset:64
	global_load_dwordx4 v[182:185], v151, s[22:23] offset:64
	s_waitcnt vmcnt(15)
	v_pk_fma_f32 v[72:73], v[72:73], v[88:89], v[188:189]
	v_pk_fma_f32 v[70:71], v[70:71], v[86:87], v[186:187]
	global_store_dwordx4 v151, v[70:73], s[100:101] offset:512
	global_load_dwordx4 v[186:189], v151, s[22:23] offset:512
	s_waitcnt vmcnt(15)
	v_pk_fma_f32 v[68:69], v[68:69], v[76:77], v[192:193]
	v_pk_fma_f32 v[66:67], v[66:67], v[74:75], v[190:191]
	global_store_dwordx4 v151, v[66:69], s[100:101] offset:576
	global_load_dwordx4 v[190:193], v151, s[22:23] offset:576
	s_add_u32 s100, s70, 0x100000
	s_addc_u32 s101, s71, 0
	s_waitcnt vmcnt(15)
	v_pk_fma_f32 v[64:65], v[64:65], v[96:97], v[220:221]
	v_pk_fma_f32 v[62:63], v[62:63], v[94:95], v[218:219]
	global_store_dwordx4 v151, v[62:65], s[100:101]
	s_waitcnt vmcnt(14)
	v_pk_fma_f32 v[60:61], v[60:61], v[92:93], v[224:225]
	v_pk_fma_f32 v[58:59], v[58:59], v[90:91], v[222:223]
	global_store_dwordx4 v151, v[58:61], s[100:101] offset:64
	s_waitcnt vmcnt(13)
	v_pk_fma_f32 v[56:57], v[56:57], v[88:89], v[228:229]
	v_pk_fma_f32 v[54:55], v[54:55], v[86:87], v[226:227]
	global_store_dwordx4 v151, v[54:57], s[100:101] offset:512
	s_waitcnt vmcnt(12)
	v_pk_fma_f32 v[52:53], v[52:53], v[76:77], v[232:233]
	v_pk_fma_f32 v[50:51], v[50:51], v[74:75], v[230:231]
	global_store_dwordx4 v151, v[50:53], s[100:101] offset:576
	s_add_u32 s100, s70, 0x120000
	s_addc_u32 s101, s71, 0
	s_waitcnt vmcnt(11)
	v_pk_fma_f32 v[48:49], v[48:49], v[96:97], v[236:237]
	v_pk_fma_f32 v[46:47], v[46:47], v[94:95], v[234:235]
	global_store_dwordx4 v151, v[46:49], s[100:101]
	s_waitcnt vmcnt(10)
	v_pk_fma_f32 v[44:45], v[44:45], v[92:93], v[240:241]
	v_pk_fma_f32 v[42:43], v[42:43], v[90:91], v[238:239]
	global_store_dwordx4 v151, v[42:45], s[100:101] offset:64
	s_waitcnt vmcnt(9)
	v_pk_fma_f32 v[40:41], v[40:41], v[88:89], v[244:245]
	v_pk_fma_f32 v[38:39], v[38:39], v[86:87], v[242:243]
	global_store_dwordx4 v151, v[38:41], s[100:101] offset:512
	s_waitcnt vmcnt(8)
	v_pk_fma_f32 v[36:37], v[36:37], v[76:77], v[248:249]
	v_pk_fma_f32 v[34:35], v[34:35], v[74:75], v[246:247]
	global_store_dwordx4 v151, v[34:37], s[100:101] offset:576
	s_add_u32 s100, s70, 0x140000
	s_addc_u32 s101, s71, 0
	s_waitcnt vmcnt(7)
	v_pk_fma_f32 v[32:33], v[32:33], v[96:97], v[160:161]
	v_pk_fma_f32 v[30:31], v[30:31], v[94:95], v[158:159]
	global_store_dwordx4 v151, v[30:33], s[100:101]
	s_waitcnt vmcnt(6)
	v_pk_fma_f32 v[28:29], v[28:29], v[92:93], v[164:165]
	v_pk_fma_f32 v[26:27], v[26:27], v[90:91], v[162:163]
	global_store_dwordx4 v151, v[26:29], s[100:101] offset:64
	s_waitcnt vmcnt(5)
	v_pk_fma_f32 v[24:25], v[24:25], v[88:89], v[168:169]
	v_pk_fma_f32 v[22:23], v[22:23], v[86:87], v[166:167]
	global_store_dwordx4 v151, v[22:25], s[100:101] offset:512
	s_waitcnt vmcnt(4)
	v_pk_fma_f32 v[20:21], v[20:21], v[76:77], v[172:173]
	v_pk_fma_f32 v[18:19], v[18:19], v[74:75], v[170:171]
	global_store_dwordx4 v151, v[18:21], s[100:101] offset:576
	s_add_u32 s100, s70, 0x160000
	s_addc_u32 s101, s71, 0
	s_waitcnt vmcnt(3)
	v_pk_fma_f32 v[16:17], v[16:17], v[96:97], v[176:177]
	v_pk_fma_f32 v[14:15], v[14:15], v[94:95], v[174:175]
	global_store_dwordx4 v151, v[14:17], s[100:101]
	s_waitcnt vmcnt(2)
	v_pk_fma_f32 v[12:13], v[12:13], v[92:93], v[184:185]
	v_pk_fma_f32 v[10:11], v[10:11], v[90:91], v[182:183]
	global_store_dwordx4 v151, v[10:13], s[100:101] offset:64
	s_waitcnt vmcnt(1)
	v_pk_fma_f32 v[8:9], v[8:9], v[88:89], v[188:189]
	v_pk_fma_f32 v[6:7], v[6:7], v[86:87], v[186:187]
	global_store_dwordx4 v151, v[6:9], s[100:101] offset:512
	s_waitcnt vmcnt(0)
	v_pk_fma_f32 v[4:5], v[4:5], v[76:77], v[192:193]
	v_pk_fma_f32 v[2:3], v[2:3], v[74:75], v[190:191]
	global_store_dwordx4 v151, v[2:5], s[100:101] offset:576
	s_mov_b64 s[22:23], -1
	s_andn2_b64 vcc, exec, s[14:15]
	s_waitcnt vmcnt(0)
	s_cbranch_vccnz .LBB0_1074
	s_andn2_b64 vcc, exec, s[0:1]
	s_cbranch_vccnz .LBB0_1073
	s_barrier
	s_branch .LBB0_1073

; __global__ void __launch_bounds__(512, 2) fwd_mega(Args a) {
	.amdhsa_kernel _Z8fwd_mega4Args
		.amdhsa_group_segment_fixed_size 0
		.amdhsa_private_segment_fixed_size 0
		.amdhsa_kernarg_size 560
		.amdhsa_user_sgpr_count 2
		.amdhsa_user_sgpr_dispatch_ptr 0
		.amdhsa_user_sgpr_queue_ptr 0
		.amdhsa_user_sgpr_kernarg_segment_ptr 1
		.amdhsa_user_sgpr_dispatch_id 0
		.amdhsa_user_sgpr_kernarg_preload_length 0
		.amdhsa_user_sgpr_kernarg_preload_offset 0
		.amdhsa_user_sgpr_private_segment_size 0
		.amdhsa_uses_dynamic_stack 0
		.amdhsa_enable_private_segment 0
		.amdhsa_system_sgpr_workgroup_id_x 1
		.amdhsa_system_sgpr_workgroup_id_y 0
		.amdhsa_system_sgpr_workgroup_id_z 0
		.amdhsa_system_sgpr_workgroup_info 0
		.amdhsa_system_vgpr_workitem_id 2
		.amdhsa_next_free_vgpr 255
		.amdhsa_next_free_sgpr 102
		.amdhsa_accum_offset 256
		.amdhsa_reserve_vcc 1
		.amdhsa_float_round_mode_32 0
		.amdhsa_float_round_mode_16_64 0
		.amdhsa_float_denorm_mode_32 3
		.amdhsa_float_denorm_mode_16_64 3
		.amdhsa_dx10_clamp 1
		.amdhsa_ieee_mode 1
		.amdhsa_fp16_overflow 0
		.amdhsa_tg_split 0
		.amdhsa_exception_fp_ieee_invalid_op 0
		.amdhsa_exception_fp_denorm_src 0
		.amdhsa_exception_fp_ieee_div_zero 0
		.amdhsa_exception_fp_ieee_overflow 0
		.amdhsa_exception_fp_ieee_underflow 0
		.amdhsa_exception_fp_ieee_inexact 0
		.amdhsa_exception_int_div_zero 0
	.end_amdhsa_kernel

; __global__ void __launch_bounds__(512, 2) fwd_mega(Args a) {
amdhsa.kernels:
  - .agpr_count:     0
    .args:
      - .offset:         0
        .size:           304
        .value_kind:     by_value
      - .offset:         304
        .size:           4
        .value_kind:     hidden_block_count_x
      - .offset:         308
        .size:           4
        .value_kind:     hidden_block_count_y
      - .offset:         312
        .size:           4
        .value_kind:     hidden_block_count_z
      - .offset:         316
        .size:           2
        .value_kind:     hidden_group_size_x
      - .offset:         318
        .size:           2
        .value_kind:     hidden_group_size_y
      - .offset:         320
        .size:           2
        .value_kind:     hidden_group_size_z
      - .offset:         322
        .size:           2
        .value_kind:     hidden_remainder_x
      - .offset:         324
        .size:           2
        .value_kind:     hidden_remainder_y
      - .offset:         326
        .size:           2
        .value_kind:     hidden_remainder_z
      - .offset:         344
        .size:           8
        .value_kind:     hidden_global_offset_x
      - .offset:         352
        .size:           8
        .value_kind:     hidden_global_offset_y
      - .offset:         360
        .size:           8
        .value_kind:     hidden_global_offset_z
      - .offset:         368
        .size:           2
        .value_kind:     hidden_grid_dims
      - .offset:         392
        .size:           8
        .value_kind:     hidden_multigrid_sync_arg
      - .offset:         424
        .size:           4
        .value_kind:     hidden_dynamic_lds_size
    .group_segment_fixed_size: 0
    .kernarg_segment_align: 8
    .kernarg_segment_size: 560
    .language:       OpenCL C
    .language_version:
      - 2
      - 0
    .max_flat_workgroup_size: 512
    .name:           _Z8fwd_mega4Args
    .private_segment_fixed_size: 0
    .sgpr_count:     108
    .sgpr_spill_count: 282
    .symbol:         _Z8fwd_mega4Args.kd
    .uniform_work_group_size: 1
    .uses_dynamic_stack: false
    .vgpr_count:     255
    .vgpr_spill_count: 0
    .wavefront_size: 64
